# lever 7 (VALU instruction count in the VALU-bound attention tile body): ALiBi C-operand init computed straight into the accumulator tuples, 30 v_mov per left-of-diagonal tile removed (bit-identical DA
# speedup vs baseline: 1.0183x; 1.0183x over previous
.LBB0_589:
	s_add_i32 s30, s21, 0xffff0000
	s_and_b32 s30, s30, 0xc000
	s_add_i32 s42, s30, 0
	v_add_u32_e32 v0, s42, v210
	s_sub_i32 s43, s28, 64
	ds_read_b128 v[6:9], v0
	ds_read_b128 v[10:13], v0 offset:8192
	v_cvt_f32_u32_e32 v0, s43
	v_add_u32_e32 v14, s42, v211
	ds_read_b128 v[224:227], v14
	ds_read_b128 v[228:231], v14 offset:8192
	s_add_i32 s36, s21, 0xfffec000
	v_sub_f32_e32 v0, v0, v205
	v_fma_f32 v112, v166, v0, -v169
	v_add_f32_e32 v128, v168, v112
	v_add_f32_e32 v129, v166, v128
	v_add_f32_e32 v130, v167, v128
	v_add_f32_e32 v131, v186, v128
	v_add_f32_e32 v132, v187, v128
	v_add_f32_e32 v133, v166, v132
	v_add_f32_e32 v134, v167, v132
	v_add_f32_e32 v135, v186, v132
	v_add_f32_e32 v136, v187, v132
	v_add_f32_e32 v137, v166, v136
	v_add_f32_e32 v138, v167, v136
	v_add_f32_e32 v139, v186, v136
	v_add_f32_e32 v140, v187, v136
	v_add_f32_e32 v141, v166, v140
	v_add_f32_e32 v142, v167, v140
	v_add_f32_e32 v143, v186, v140
	v_add_f32_e32 v113, v166, v112
	v_add_f32_e32 v114, v167, v112
	v_add_f32_e32 v115, v186, v112
	v_add_f32_e32 v116, v187, v112
	v_add_f32_e32 v117, v166, v116
	v_add_f32_e32 v118, v167, v116
	v_add_f32_e32 v119, v186, v116
	v_add_f32_e32 v120, v187, v116
	v_add_f32_e32 v121, v166, v120
	v_add_f32_e32 v122, v167, v120
	v_add_f32_e32 v123, v186, v120
	v_add_f32_e32 v124, v187, v120
	v_add_f32_e32 v125, v166, v124
	v_add_f32_e32 v126, v167, v124
	v_add_f32_e32 v127, v186, v124
	s_waitcnt lgkmcnt(2)
	v_mfma_f32_32x32x16_bf16 v[128:143], v[10:13], v[144:147], v[128:143]
	v_add_u32_e32 v0, s42, v212
	s_and_b32 s36, s36, 0x8000
	v_exp_f32_e32 v96, v96
	v_exp_f32_e32 v14, v97
	v_exp_f32_e32 v80, v80
	v_exp_f32_e32 v98, v98
	v_exp_f32_e32 v82, v82
	v_mfma_f32_32x32x16_bf16 v[112:127], v[6:9], v[144:147], v[112:127]
	ds_read_b128 v[6:9], v0
	ds_read_b128 v[10:13], v0 offset:8192
	v_add_u32_e32 v0, s42, v213
	v_exp_f32_e32 v248, v99
	v_exp_f32_e32 v250, v83
	v_exp_f32_e32 v83, v84
	v_exp_f32_e32 v84, v86
	v_exp_f32_e32 v196, v103
	s_waitcnt lgkmcnt(3)
	v_mfma_f32_32x32x16_bf16 v[112:127], v[224:227], v[148:151], v[112:127]
	ds_read_b128 v[224:227], v0
	ds_read_b128 v[232:235], v0 offset:8192
	v_add_u32_e32 v0, s36, v204
	ds_read_b128 v[236:239], v0
	ds_read_b128 v[240:243], v0 offset:4096
	v_exp_f32_e32 v86, v106
	v_exp_f32_e32 v198, v105
	v_exp_f32_e32 v106, v89
	v_exp_f32_e32 v164, v107
	s_waitcnt lgkmcnt(6)
	v_mfma_f32_32x32x16_bf16 v[128:143], v[228:231], v[148:151], v[128:143]
	ds_read_b128 v[228:231], v0 offset:8192
	ds_read_b128 v[244:247], v0 offset:12288
	v_exp_f32_e32 v0, v81
	v_exp_f32_e32 v81, v104
	v_exp_f32_e32 v104, v87
	v_exp_f32_e32 v87, v90
	v_exp_f32_e32 v160, v91
	v_exp_f32_e32 v89, v92
	s_waitcnt lgkmcnt(7)
	v_mfma_f32_32x32x16_bf16 v[112:127], v[6:9], v[152:155], v[112:127]
	v_exp_f32_e32 v8, v100
	v_exp_f32_e32 v9, v102
	v_exp_f32_e32 v90, v110
	v_exp_f32_e32 v91, v94
	v_exp_f32_e32 v162, v109
	v_exp_f32_e32 v200, v111
	v_exp_f32_e32 v110, v95
	s_waitcnt lgkmcnt(6)
	v_mfma_f32_32x32x16_bf16 v[128:143], v[10:13], v[152:155], v[128:143]
	v_cvt_pk_bf16_f32 v6, v96, v14
	v_add_f32_e32 v15, v96, v80
	v_add_f32_e32 v249, v98, v82
	v_add_f32_e32 v197, v9, v84
	v_add_f32_e32 v165, v86, v87
	v_add_f32_e32 v201, v90, v91
	v_cvt_pk_bf16_f32 v7, v98, v248
	s_waitcnt lgkmcnt(5)
	v_mfma_f32_32x32x16_bf16 v[112:127], v[224:227], v[156:159], v[112:127]
	v_exp_f32_e32 v224, v101
	v_exp_f32_e32 v226, v85
	v_exp_f32_e32 v85, v88
	v_exp_f32_e32 v88, v108
	v_exp_f32_e32 v108, v93
	v_add_f32_e32 v225, v8, v83
	v_add_f32_e32 v199, v81, v85
	s_waitcnt lgkmcnt(4)
	v_mfma_f32_32x32x16_bf16 v[128:143], v[232:235], v[156:159], v[128:143]
	v_add_f32_e32 v163, v88, v89
	v_cvt_pk_bf16_f32 v8, v8, v224
	v_cvt_pk_bf16_f32 v9, v9, v196
	v_cvt_pk_bf16_f32 v10, v81, v198
	v_cvt_pk_bf16_f32 v11, v86, v164
	v_cvt_pk_bf16_f32 v12, v88, v162
	v_cvt_pk_bf16_f32 v13, v90, v200
	v_cvt_pk_bf16_f32 v80, v80, v0
	v_cvt_pk_bf16_f32 v81, v82, v250
	v_cvt_pk_bf16_f32 v82, v83, v226
	v_cvt_pk_bf16_f32 v83, v84, v104
	v_cvt_pk_bf16_f32 v84, v85, v106
	v_cvt_pk_bf16_f32 v85, v87, v160
	v_cvt_pk_bf16_f32 v86, v89, v108
	v_cvt_pk_bf16_f32 v87, v91, v110
	v_add_f32_e32 v14, v14, v0
	v_add_f32_e32 v15, v15, v1
	v_add_u32_e32 v100, s36, v220
	v_add_f32_e32 v251, v14, v15
	v_add_f32_e32 v14, v248, v250
	v_add_f32_e32 v15, v249, v251
	s_waitcnt lgkmcnt(3)
	v_mfma_f32_32x32x16_bf16 v[64:79], v[236:239], v[6:9], v[64:79]
	v_add_f32_e32 v227, v14, v15
	v_add_f32_e32 v14, v224, v226
	v_add_f32_e32 v15, v225, v227
	ds_read_b128 v[88:91], v100
	ds_read_b128 v[92:95], v100 offset:4096
	ds_read_b128 v[96:99], v100 offset:8192
	ds_read_b128 v[100:103], v100 offset:12288
	v_add_f32_e32 v105, v14, v15
	v_add_f32_e32 v14, v196, v104
	v_add_f32_e32 v15, v197, v105
	s_waitcnt lgkmcnt(6)
	v_mfma_f32_32x32x16_bf16 v[48:63], v[240:243], v[6:9], v[48:63]
	v_add_f32_e32 v107, v14, v15
	v_add_f32_e32 v14, v198, v106
	v_add_f32_e32 v15, v199, v107
	s_nop 0
	v_add_f32_e32 v161, v14, v15
	v_add_f32_e32 v14, v164, v160
	v_add_f32_e32 v15, v165, v161
	s_waitcnt lgkmcnt(5)
	v_mfma_f32_32x32x16_bf16 v[32:47], v[228:231], v[6:9], v[32:47]
	v_add_f32_e32 v109, v14, v15
	v_add_f32_e32 v14, v162, v108
	v_add_f32_e32 v15, v163, v109
	s_nop 0
	v_add_f32_e32 v111, v14, v15
	v_add_f32_e32 v14, v200, v110
	v_add_f32_e32 v15, v201, v111
	s_waitcnt lgkmcnt(4)
	v_mfma_f32_32x32x16_bf16 v[16:31], v[244:247], v[6:9], v[16:31]
	v_add_f32_e32 v0, v14, v15
	v_add_f32_e32 v6, v184, v0
	s_waitcnt lgkmcnt(3)
	v_mfma_f32_32x32x16_bf16 v[64:79], v[88:91], v[10:13], v[64:79]
	v_add_u32_e32 v0, s36, v221
	s_waitcnt lgkmcnt(2)
	v_mfma_f32_32x32x16_bf16 v[48:63], v[92:95], v[10:13], v[48:63]
	s_waitcnt lgkmcnt(1)
	v_mfma_f32_32x32x16_bf16 v[32:47], v[96:99], v[10:13], v[32:47]
	ds_read_b128 v[88:91], v0
	ds_read_b128 v[92:95], v0 offset:4096
	ds_read_b128 v[96:99], v0 offset:8192
	ds_read_b128 v[104:107], v0 offset:12288
	s_waitcnt lgkmcnt(4)
	v_mfma_f32_32x32x16_bf16 v[16:31], v[100:103], v[10:13], v[16:31]
	v_add_u32_e32 v0, s36, v222
	ds_read_b128 v[8:11], v0
	ds_read_b128 v[12:15], v0 offset:4096
	s_waitcnt lgkmcnt(5)
	v_mfma_f32_32x32x16_bf16 v[64:79], v[88:91], v[80:83], v[64:79]
	ds_read_b128 v[88:91], v0 offset:8192
	ds_read_b128 v[100:103], v0 offset:12288
	v_max_f32_e32 v0, v113, v113
	v_max_f32_e32 v7, v129, v129
	v_max_f32_e32 v0, v0, v7
	v_max3_f32 v7, v112, v128, v114
	v_max3_f32 v0, v0, v115, v131
	v_max3_f32 v7, v7, v130, v116
	v_max3_f32 v0, v0, v117, v133
	s_waitcnt lgkmcnt(6)
	v_mfma_f32_32x32x16_bf16 v[48:63], v[92:95], v[80:83], v[48:63]
	v_max3_f32 v7, v7, v132, v118
	v_max3_f32 v0, v0, v119, v135
	v_max3_f32 v7, v7, v134, v120
	v_max3_f32 v0, v0, v121, v137
	v_max3_f32 v7, v7, v136, v122
	v_max3_f32 v0, v0, v123, v139
	v_max3_f32 v7, v7, v138, v124
	s_waitcnt lgkmcnt(5)
	v_mfma_f32_32x32x16_bf16 v[32:47], v[96:99], v[80:83], v[32:47]
	v_max3_f32 v0, v0, v125, v141
	v_max3_f32 v7, v7, v140, v126
	v_max3_f32 v0, v0, v127, v143
	v_max3_f32 v0, v7, v142, v0
	v_mov_b32_e32 v7, v0
	s_nop 1
	v_permlane32_swap_b32_e32 v0, v7
	s_waitcnt lgkmcnt(4)
	v_mfma_f32_32x32x16_bf16 v[16:31], v[104:107], v[80:83], v[16:31]
	s_waitcnt lgkmcnt(3)
	v_mfma_f32_32x32x16_bf16 v[64:79], v[8:11], v[84:87], v[64:79]
	v_max_f32_e32 v7, v7, v7
	v_max_f32_e32 v0, v0, v0
	v_max_f32_e32 v0, v0, v7
	v_cmp_lt_f32_e32 vcc, s93, v0
	s_waitcnt lgkmcnt(2)
	v_mfma_f32_32x32x16_bf16 v[48:63], v[12:15], v[84:87], v[48:63]
	s_waitcnt lgkmcnt(1)
	v_mfma_f32_32x32x16_bf16 v[32:47], v[88:91], v[84:87], v[32:47]
	s_waitcnt lgkmcnt(0)
	v_mfma_f32_32x32x16_bf16 v[16:31], v[100:103], v[84:87], v[16:31]
	s_cbranch_vccz .LBB0_591
	v_max_f32_e32 v0, v0, v0
	v_max_f32_e32 v7, 0, v0
	v_exp_f32_e64 v0, -v7
	v_add_f32_e32 v169, v169, v7
	v_sub_f32_e32 v127, v127, v7
	v_sub_f32_e32 v126, v126, v7
	v_pk_mul_f32 v[78:79], v[78:79], v[0:1] op_sel_hi:[1,0]
	v_pk_mul_f32 v[76:77], v[76:77], v[0:1] op_sel_hi:[1,0]
	v_pk_mul_f32 v[74:75], v[74:75], v[0:1] op_sel_hi:[1,0]
	v_pk_mul_f32 v[72:73], v[72:73], v[0:1] op_sel_hi:[1,0]
	v_pk_mul_f32 v[70:71], v[70:71], v[0:1] op_sel_hi:[1,0]
	v_pk_mul_f32 v[68:69], v[68:69], v[0:1] op_sel_hi:[1,0]
	v_pk_mul_f32 v[66:67], v[66:67], v[0:1] op_sel_hi:[1,0]
	v_pk_mul_f32 v[64:65], v[64:65], v[0:1] op_sel_hi:[1,0]
	v_pk_mul_f32 v[62:63], v[62:63], v[0:1] op_sel_hi:[1,0]
	v_pk_mul_f32 v[60:61], v[60:61], v[0:1] op_sel_hi:[1,0]
	v_pk_mul_f32 v[58:59], v[58:59], v[0:1] op_sel_hi:[1,0]
	v_pk_mul_f32 v[56:57], v[56:57], v[0:1] op_sel_hi:[1,0]
	v_pk_mul_f32 v[54:55], v[54:55], v[0:1] op_sel_hi:[1,0]
	v_pk_mul_f32 v[52:53], v[52:53], v[0:1] op_sel_hi:[1,0]
	v_pk_mul_f32 v[50:51], v[50:51], v[0:1] op_sel_hi:[1,0]
	v_pk_mul_f32 v[48:49], v[48:49], v[0:1] op_sel_hi:[1,0]
	v_pk_mul_f32 v[46:47], v[0:1], v[46:47] op_sel_hi:[0,1]
	v_pk_mul_f32 v[44:45], v[0:1], v[44:45] op_sel_hi:[0,1]
	v_pk_mul_f32 v[42:43], v[0:1], v[42:43] op_sel_hi:[0,1]
	v_pk_mul_f32 v[40:41], v[0:1], v[40:41] op_sel_hi:[0,1]
	v_pk_mul_f32 v[38:39], v[0:1], v[38:39] op_sel_hi:[0,1]
	v_pk_mul_f32 v[36:37], v[0:1], v[36:37] op_sel_hi:[0,1]
	v_pk_mul_f32 v[34:35], v[0:1], v[34:35] op_sel_hi:[0,1]
	v_pk_mul_f32 v[32:33], v[0:1], v[32:33] op_sel_hi:[0,1]
	v_pk_mul_f32 v[30:31], v[0:1], v[30:31] op_sel_hi:[0,1]
	v_pk_mul_f32 v[28:29], v[0:1], v[28:29] op_sel_hi:[0,1]
	v_pk_mul_f32 v[26:27], v[0:1], v[26:27] op_sel_hi:[0,1]
	v_pk_mul_f32 v[24:25], v[0:1], v[24:25] op_sel_hi:[0,1]
	v_pk_mul_f32 v[22:23], v[0:1], v[22:23] op_sel_hi:[0,1]
	v_pk_mul_f32 v[20:21], v[0:1], v[20:21] op_sel_hi:[0,1]
	v_pk_mul_f32 v[18:19], v[0:1], v[18:19] op_sel_hi:[0,1]
	v_pk_mul_f32 v[16:17], v[0:1], v[16:17] op_sel_hi:[0,1]
	v_sub_f32_e32 v125, v125, v7
	v_sub_f32_e32 v124, v124, v7
	v_sub_f32_e32 v123, v123, v7
	v_sub_f32_e32 v122, v122, v7
	v_sub_f32_e32 v121, v121, v7
	v_sub_f32_e32 v120, v120, v7
	v_sub_f32_e32 v119, v119, v7
	v_sub_f32_e32 v118, v118, v7
	v_sub_f32_e32 v117, v117, v7
	v_sub_f32_e32 v116, v116, v7
	v_sub_f32_e32 v115, v115, v7
	v_sub_f32_e32 v114, v114, v7
	v_sub_f32_e32 v113, v113, v7
	v_sub_f32_e32 v112, v112, v7
	v_sub_f32_e32 v143, v143, v7
	v_sub_f32_e32 v142, v142, v7
	v_sub_f32_e32 v141, v141, v7
	v_sub_f32_e32 v140, v140, v7
	v_sub_f32_e32 v139, v139, v7
	v_sub_f32_e32 v138, v138, v7
	v_sub_f32_e32 v137, v137, v7
	v_sub_f32_e32 v136, v136, v7
	v_sub_f32_e32 v135, v135, v7
	v_sub_f32_e32 v134, v134, v7
	v_sub_f32_e32 v133, v133, v7
	v_sub_f32_e32 v132, v132, v7
	v_sub_f32_e32 v131, v131, v7
	v_sub_f32_e32 v130, v130, v7
	v_sub_f32_e32 v129, v129, v7
	v_sub_f32_e32 v128, v128, v7
	v_mul_f32_e32 v6, v6, v0

.LBB0_595:
	s_add_i32 s36, s21, 0xffff4000
	s_and_b32 s36, s36, 0x8000
	s_add_i32 s36, s36, 0
	v_add_u32_e32 v0, s36, v210
	ds_read_b128 v[2:5], v0
	ds_read_b128 v[8:11], v0 offset:8192
	v_cvt_f32_u32_e32 v0, s28
	v_add_u32_e32 v7, s36, v211
	ds_read_b128 v[12:15], v7
	ds_read_b128 v[224:227], v7 offset:8192
	v_sub_f32_e32 v0, v0, v205
	v_fma_f32 v96, v166, v0, -v169
	v_add_f32_e32 v80, v168, v96
	v_add_f32_e32 v81, v166, v80
	v_add_f32_e32 v82, v167, v80
	v_add_f32_e32 v83, v186, v80
	v_add_f32_e32 v84, v187, v80
	v_add_f32_e32 v85, v166, v84
	v_add_f32_e32 v86, v167, v84
	v_add_f32_e32 v87, v186, v84
	v_add_f32_e32 v88, v187, v84
	v_add_f32_e32 v89, v166, v88
	v_add_f32_e32 v90, v167, v88
	v_add_f32_e32 v91, v186, v88
	v_add_f32_e32 v92, v187, v88
	v_add_f32_e32 v93, v166, v92
	v_add_f32_e32 v94, v167, v92
	v_add_f32_e32 v95, v186, v92
	v_add_f32_e32 v97, v166, v96
	v_add_f32_e32 v98, v167, v96
	v_add_f32_e32 v99, v186, v96
	v_add_f32_e32 v100, v187, v96
	v_add_f32_e32 v101, v166, v100
	v_add_f32_e32 v102, v167, v100
	v_add_f32_e32 v103, v186, v100
	v_add_f32_e32 v104, v187, v100
	v_add_f32_e32 v105, v166, v104
	v_add_f32_e32 v106, v167, v104
	v_add_f32_e32 v107, v186, v104
	v_add_f32_e32 v108, v187, v104
	v_add_f32_e32 v109, v166, v108
	v_add_f32_e32 v110, v167, v108
	v_add_f32_e32 v111, v186, v108
	s_waitcnt lgkmcnt(3)
	v_mfma_f32_32x32x16_bf16 v[96:111], v[2:5], v[144:147], v[96:111]
	v_add_u32_e32 v0, s36, v212
	v_exp_f32_e32 v7, v112
	v_exp_f32_e32 v112, v128
	v_exp_f32_e32 v160, v129
	v_exp_f32_e32 v116, v116
	v_exp_f32_e32 v128, v132
	v_exp_f32_e32 v132, v115
	s_waitcnt lgkmcnt(2)
	v_mfma_f32_32x32x16_bf16 v[80:95], v[8:11], v[144:147], v[80:95]
	ds_read_b128 v[2:5], v0
	ds_read_b128 v[8:11], v0 offset:8192
	v_add_u32_e32 v0, s36, v213
	v_exp_f32_e32 v162, v131
	v_exp_f32_e32 v115, v134
	v_exp_f32_e32 v134, v117
	v_exp_f32_e32 v164, v133
	v_exp_f32_e32 v198, v119
	s_waitcnt lgkmcnt(3)
	v_mfma_f32_32x32x16_bf16 v[96:111], v[12:15], v[148:151], v[96:111]
	ds_read_b128 v[12:15], v0
	ds_read_b128 v[228:231], v0 offset:8192
	v_add_u32_e32 v0, s30, v204
	ds_read_b128 v[232:235], v0
	ds_read_b128 v[236:239], v0 offset:4096
	v_exp_f32_e32 v117, v136
	v_exp_f32_e32 v196, v135
	v_exp_f32_e32 v136, v121
	v_exp_f32_e32 v200, v137
	s_waitcnt lgkmcnt(6)
	v_mfma_f32_32x32x16_bf16 v[80:95], v[224:227], v[148:151], v[80:95]
	ds_read_b128 v[224:227], v0 offset:8192
	ds_read_b128 v[240:243], v0 offset:12288
	v_exp_f32_e32 v0, v113
	v_exp_f32_e32 v113, v114
	v_exp_f32_e32 v114, v130
	v_exp_f32_e32 v244, v139
	v_exp_f32_e32 v119, v140
	v_exp_f32_e32 v140, v125
	s_waitcnt lgkmcnt(7)
	v_mfma_f32_32x32x16_bf16 v[96:111], v[2:5], v[152:155], v[96:111]
	v_exp_f32_e32 v5, v118
	v_exp_f32_e32 v118, v138
	v_exp_f32_e32 v138, v123
	v_exp_f32_e32 v246, v141
	v_exp_f32_e32 v248, v143
	v_add_f32_e32 v161, v112, v7
	v_add_f32_e32 v163, v114, v113
	s_waitcnt lgkmcnt(6)
	v_mfma_f32_32x32x16_bf16 v[80:95], v[8:11], v[152:155], v[80:95]
	v_add_f32_e32 v165, v128, v116
	v_add_f32_e32 v197, v115, v5
	v_cvt_pk_bf16_f32 v2, v7, v0
	v_cvt_pk_bf16_f32 v3, v113, v132
	v_cvt_pk_bf16_f32 v4, v116, v134
	v_cvt_pk_bf16_f32 v5, v5, v198
	v_cvt_pk_bf16_f32 v113, v118, v244
	s_waitcnt lgkmcnt(5)
	v_mfma_f32_32x32x16_bf16 v[96:111], v[12:15], v[156:159], v[96:111]
	v_exp_f32_e32 v12, v120
	v_exp_f32_e32 v13, v122
	v_exp_f32_e32 v14, v124
	v_exp_f32_e32 v15, v126
	v_exp_f32_e32 v120, v142
	v_exp_f32_e32 v142, v127
	v_add_f32_e32 v201, v117, v12
	s_waitcnt lgkmcnt(4)
	v_mfma_f32_32x32x16_bf16 v[80:95], v[228:231], v[156:159], v[80:95]
	v_add_f32_e32 v245, v118, v13
	v_add_f32_e32 v247, v119, v14
	v_add_f32_e32 v249, v120, v15
	v_cvt_pk_bf16_f32 v8, v12, v136
	v_cvt_pk_bf16_f32 v9, v13, v138
	v_cvt_pk_bf16_f32 v10, v14, v140
	v_cvt_pk_bf16_f32 v11, v15, v142
	v_cvt_pk_bf16_f32 v12, v112, v160
	v_cvt_pk_bf16_f32 v13, v114, v162
	v_cvt_pk_bf16_f32 v14, v128, v164
	v_cvt_pk_bf16_f32 v15, v115, v196
	v_cvt_pk_bf16_f32 v112, v117, v200
	v_cvt_pk_bf16_f32 v114, v119, v246
	v_cvt_pk_bf16_f32 v115, v120, v248
	v_add_f32_e32 v160, v160, v0
	v_add_f32_e32 v161, v161, v1
	v_add_u32_e32 v7, s30, v220
	v_add_f32_e32 v161, v160, v161
	v_add_f32_e32 v160, v160, v160
	v_mov_b32_e32 v133, v161
	v_add_f32_e32 v132, v162, v132
	v_add_f32_e32 v133, v163, v133
	s_waitcnt lgkmcnt(3)
	v_mfma_f32_32x32x16_bf16 v[64:79], v[232:235], v[2:5], v[64:79]
	v_add_f32_e32 v135, v132, v133
	v_add_f32_e32 v132, v164, v134
	v_add_f32_e32 v133, v165, v135
	ds_read_b128 v[116:119], v7
	ds_read_b128 v[120:123], v7 offset:4096
	ds_read_b128 v[124:127], v7 offset:8192
	ds_read_b128 v[128:131], v7 offset:12288
	v_add_f32_e32 v199, v132, v133
	v_add_f32_e32 v132, v196, v198
	v_add_f32_e32 v133, v197, v199
	s_waitcnt lgkmcnt(6)
	v_mfma_f32_32x32x16_bf16 v[48:63], v[236:239], v[2:5], v[48:63]
	v_add_f32_e32 v137, v132, v133
	v_add_f32_e32 v132, v200, v136
	v_add_f32_e32 v133, v201, v137
	s_nop 0
	v_add_f32_e32 v139, v132, v133
	v_add_f32_e32 v132, v244, v138
	v_add_f32_e32 v133, v245, v139
	s_waitcnt lgkmcnt(5)
	v_mfma_f32_32x32x16_bf16 v[32:47], v[224:227], v[2:5], v[32:47]
	v_add_f32_e32 v141, v132, v133
	v_add_f32_e32 v132, v246, v140
	v_add_f32_e32 v133, v247, v141
	s_nop 0
	v_add_f32_e32 v143, v132, v133
	v_add_f32_e32 v132, v248, v142
	v_add_f32_e32 v133, v249, v143
	s_waitcnt lgkmcnt(4)
	v_mfma_f32_32x32x16_bf16 v[16:31], v[240:243], v[2:5], v[16:31]
	v_add_f32_e32 v0, v132, v133
	v_add_f32_e32 v184, v6, v0
	s_waitcnt lgkmcnt(3)
	v_mfma_f32_32x32x16_bf16 v[64:79], v[116:119], v[8:11], v[64:79]
	v_add_u32_e32 v0, s30, v221
	s_waitcnt lgkmcnt(2)
	v_mfma_f32_32x32x16_bf16 v[48:63], v[120:123], v[8:11], v[48:63]
	s_waitcnt lgkmcnt(1)
	v_mfma_f32_32x32x16_bf16 v[32:47], v[124:127], v[8:11], v[32:47]
	ds_read_b128 v[2:5], v0
	ds_read_b128 v[116:119], v0 offset:4096
	ds_read_b128 v[120:123], v0 offset:8192
	ds_read_b128 v[124:127], v0 offset:12288
	s_waitcnt lgkmcnt(4)
	v_mfma_f32_32x32x16_bf16 v[16:31], v[128:131], v[8:11], v[16:31]
	v_add_u32_e32 v0, s30, v222
	ds_read_b128 v[6:9], v0
	ds_read_b128 v[128:131], v0 offset:4096
	s_waitcnt lgkmcnt(5)
	v_mfma_f32_32x32x16_bf16 v[64:79], v[2:5], v[12:15], v[64:79]
	ds_read_b128 v[2:5], v0 offset:8192
	ds_read_b128 v[132:135], v0 offset:12288
	v_max_f32_e32 v0, v97, v97
	v_max_f32_e32 v10, v81, v81
	v_max_f32_e32 v0, v0, v10
	v_max3_f32 v10, v96, v80, v98
	v_max3_f32 v0, v0, v99, v83
	v_max3_f32 v10, v10, v82, v100
	v_max3_f32 v0, v0, v101, v85
	s_waitcnt lgkmcnt(6)
	v_mfma_f32_32x32x16_bf16 v[48:63], v[116:119], v[12:15], v[48:63]
	v_max3_f32 v10, v10, v84, v102
	v_max3_f32 v0, v0, v103, v87
	v_max3_f32 v10, v10, v86, v104
	v_max3_f32 v0, v0, v105, v89
	v_max3_f32 v10, v10, v88, v106
	v_max3_f32 v0, v0, v107, v91
	v_max3_f32 v10, v10, v90, v108
	s_waitcnt lgkmcnt(5)
	v_mfma_f32_32x32x16_bf16 v[32:47], v[120:123], v[12:15], v[32:47]
	v_max3_f32 v0, v0, v109, v93
	v_max3_f32 v10, v10, v92, v110
	v_max3_f32 v0, v0, v111, v95
	v_max3_f32 v0, v10, v94, v0
	v_mov_b32_e32 v10, v0
	s_nop 1
	v_permlane32_swap_b32_e32 v0, v10
	s_waitcnt lgkmcnt(4)
	v_mfma_f32_32x32x16_bf16 v[16:31], v[124:127], v[12:15], v[16:31]
	s_waitcnt lgkmcnt(3)
	v_mfma_f32_32x32x16_bf16 v[64:79], v[6:9], v[112:115], v[64:79]
	v_max_f32_e32 v0, v0, v0
	s_waitcnt lgkmcnt(2)
	v_mfma_f32_32x32x16_bf16 v[48:63], v[128:131], v[112:115], v[48:63]
	s_waitcnt lgkmcnt(1)
	v_mfma_f32_32x32x16_bf16 v[32:47], v[2:5], v[112:115], v[32:47]
	v_max_f32_e32 v2, v10, v10
	v_max_f32_e32 v0, v0, v2
	v_cmp_lt_f32_e32 vcc, s93, v0
	s_waitcnt lgkmcnt(0)
	v_mfma_f32_32x32x16_bf16 v[16:31], v[132:135], v[112:115], v[16:31]
	s_cbranch_vccz .LBB0_597
	v_max_f32_e32 v0, v0, v0
	v_max_f32_e32 v2, 0, v0
	v_exp_f32_e64 v0, -v2
	v_add_f32_e32 v169, v169, v2
	v_sub_f32_e32 v111, v111, v2
	v_sub_f32_e32 v110, v110, v2
	v_pk_mul_f32 v[78:79], v[78:79], v[0:1] op_sel_hi:[1,0]
	v_pk_mul_f32 v[76:77], v[76:77], v[0:1] op_sel_hi:[1,0]
	v_pk_mul_f32 v[74:75], v[74:75], v[0:1] op_sel_hi:[1,0]
	v_pk_mul_f32 v[72:73], v[72:73], v[0:1] op_sel_hi:[1,0]
	v_pk_mul_f32 v[70:71], v[70:71], v[0:1] op_sel_hi:[1,0]
	v_pk_mul_f32 v[68:69], v[68:69], v[0:1] op_sel_hi:[1,0]
	v_pk_mul_f32 v[66:67], v[66:67], v[0:1] op_sel_hi:[1,0]
	v_pk_mul_f32 v[64:65], v[64:65], v[0:1] op_sel_hi:[1,0]
	v_pk_mul_f32 v[62:63], v[62:63], v[0:1] op_sel_hi:[1,0]
	v_pk_mul_f32 v[60:61], v[60:61], v[0:1] op_sel_hi:[1,0]
	v_pk_mul_f32 v[58:59], v[58:59], v[0:1] op_sel_hi:[1,0]
	v_pk_mul_f32 v[56:57], v[56:57], v[0:1] op_sel_hi:[1,0]
	v_pk_mul_f32 v[54:55], v[54:55], v[0:1] op_sel_hi:[1,0]
	v_pk_mul_f32 v[52:53], v[52:53], v[0:1] op_sel_hi:[1,0]
	v_pk_mul_f32 v[50:51], v[50:51], v[0:1] op_sel_hi:[1,0]
	v_pk_mul_f32 v[48:49], v[48:49], v[0:1] op_sel_hi:[1,0]
	v_pk_mul_f32 v[46:47], v[0:1], v[46:47] op_sel_hi:[0,1]
	v_pk_mul_f32 v[44:45], v[0:1], v[44:45] op_sel_hi:[0,1]
	v_pk_mul_f32 v[42:43], v[0:1], v[42:43] op_sel_hi:[0,1]
	v_pk_mul_f32 v[40:41], v[0:1], v[40:41] op_sel_hi:[0,1]
	v_pk_mul_f32 v[38:39], v[0:1], v[38:39] op_sel_hi:[0,1]
	v_pk_mul_f32 v[36:37], v[0:1], v[36:37] op_sel_hi:[0,1]
	v_pk_mul_f32 v[34:35], v[0:1], v[34:35] op_sel_hi:[0,1]
	v_pk_mul_f32 v[32:33], v[0:1], v[32:33] op_sel_hi:[0,1]
	v_pk_mul_f32 v[30:31], v[0:1], v[30:31] op_sel_hi:[0,1]
	v_pk_mul_f32 v[28:29], v[0:1], v[28:29] op_sel_hi:[0,1]
	v_pk_mul_f32 v[26:27], v[0:1], v[26:27] op_sel_hi:[0,1]
	v_pk_mul_f32 v[24:25], v[0:1], v[24:25] op_sel_hi:[0,1]
	v_pk_mul_f32 v[22:23], v[0:1], v[22:23] op_sel_hi:[0,1]
	v_pk_mul_f32 v[20:21], v[0:1], v[20:21] op_sel_hi:[0,1]
	v_pk_mul_f32 v[18:19], v[0:1], v[18:19] op_sel_hi:[0,1]
	v_pk_mul_f32 v[16:17], v[0:1], v[16:17] op_sel_hi:[0,1]
	v_sub_f32_e32 v109, v109, v2
	v_sub_f32_e32 v108, v108, v2
	v_sub_f32_e32 v107, v107, v2
	v_sub_f32_e32 v106, v106, v2
	v_sub_f32_e32 v105, v105, v2
	v_sub_f32_e32 v104, v104, v2
	v_sub_f32_e32 v103, v103, v2
	v_sub_f32_e32 v102, v102, v2
	v_sub_f32_e32 v101, v101, v2
	v_sub_f32_e32 v100, v100, v2
	v_sub_f32_e32 v99, v99, v2
	v_sub_f32_e32 v98, v98, v2
	v_sub_f32_e32 v97, v97, v2
	v_sub_f32_e32 v96, v96, v2
	v_sub_f32_e32 v95, v95, v2
	v_sub_f32_e32 v94, v94, v2
	v_sub_f32_e32 v93, v93, v2
	v_sub_f32_e32 v92, v92, v2
	v_sub_f32_e32 v91, v91, v2
	v_sub_f32_e32 v90, v90, v2
	v_sub_f32_e32 v89, v89, v2
	v_sub_f32_e32 v88, v88, v2
	v_sub_f32_e32 v87, v87, v2
	v_sub_f32_e32 v86, v86, v2
	v_sub_f32_e32 v85, v85, v2
	v_sub_f32_e32 v84, v84, v2
	v_sub_f32_e32 v83, v83, v2
	v_sub_f32_e32 v82, v82, v2
	v_sub_f32_e32 v81, v81, v2
	v_sub_f32_e32 v80, v80, v2
	v_mul_f32_e32 v184, v184, v0
